# final norm: split-K partial slabs of the sample rows folded with batched loads instead of serialized round trips
# speedup vs baseline: 1.0311x; 1.0016x over previous
; __device__ __forceinline__ void phase_norm(PP P, int l, int which, int nsl, const float* fgate, float fscale, const Ids I) {
;     ...
;         for (int j = 0; j < 2; ++j) { const int row = rows[j];
;             const float* xr = from_in ? (row < MTP ? P->in[I_XP] + (size_t)row * D : P->in[I_XS] + (size_t)(row - MTP) * D) : xb + (size_t)row * D;
; #pragma unroll
;             for (int i = 0; i < 4; ++i) v[j][i] = *(const f32x4*)(xr + lane * 4 + 256 * i);
;             if (nsl > 0 && row >= MTP && !(j == 1 && row == row0)) {
;                 const float* pp = (const float*)(P->ws + WS_R2) + (size_t)(row - MTP) * D + lane * 4; const float* gp = fgate + (size_t)mod_row(row) * 9216 + lane * 4;
; #pragma unroll
;                 for (int i = 0; i < 4; ++i) { f32x4 a = (f32x4){0.f, 0.f, 0.f, 0.f};
;                     for (int sl = 0; sl < nsl; ++sl) a += *(const f32x4*)(pp + (size_t)sl * MTS * D + 256 * i);
;                     v[j][i] += (*(const f32x4*)(gp + 256 * i) * fscale) * a;
.LBB0_21:
	global_load_dwordx4 v[12:15], v[44:45], off offset:-3072
	global_load_dwordx4 v[8:11], v[44:45], off offset:-2048
	global_load_dwordx4 v[4:7], v[44:45], off offset:-1024
	global_load_dwordx4 v[0:3], v[44:45], off
	s_add_i32 s3, s54, 0x4000
	s_cmpk_lt_i32 s3, 0x4000
	s_cbranch_scc1 .LBB0_23
	s_lshl_b64 s[6:7], s[54:55], 12
	v_lshl_add_u64 v[20:21], v[36:37], 0, s[6:7]
	s_lshr_b32 s6, s54, 2
	s_add_i32 s6, s6, 8
	v_mad_u64_u32 v[16:17], s[6:7], s6, v184, v[38:39]
	global_load_dwordx4 v[152:155], v[16:17], off
	global_load_dwordx4 v[156:159], v[16:17], off offset:1024
	global_load_dwordx4 v[160:163], v[16:17], off offset:2048
	global_load_dwordx4 v[164:167], v[16:17], off offset:3072
	v_mov_b32_e32 v18, v20
	v_mov_b32_e32 v19, v21
	global_load_dwordx4 v[92:95], v[18:19], off
	global_load_dwordx4 v[188:191], v[18:19], off offset:1024
	v_lshl_add_u64 v[18:19], v[18:19], 0, s[82:83]
	global_load_dwordx4 v[96:99], v[18:19], off
	global_load_dwordx4 v[192:195], v[18:19], off offset:1024
	v_lshl_add_u64 v[18:19], v[18:19], 0, s[82:83]
	global_load_dwordx4 v[100:103], v[18:19], off
	global_load_dwordx4 v[196:199], v[18:19], off offset:1024
	v_lshl_add_u64 v[18:19], v[18:19], 0, s[82:83]
	global_load_dwordx4 v[104:107], v[18:19], off
	global_load_dwordx4 v[200:203], v[18:19], off offset:1024
	v_lshl_add_u64 v[18:19], v[18:19], 0, s[82:83]
	global_load_dwordx4 v[108:111], v[18:19], off
	global_load_dwordx4 v[204:207], v[18:19], off offset:1024
	v_lshl_add_u64 v[18:19], v[18:19], 0, s[82:83]
	global_load_dwordx4 v[112:115], v[18:19], off
	global_load_dwordx4 v[208:211], v[18:19], off offset:1024
	v_lshl_add_u64 v[18:19], v[18:19], 0, s[82:83]
	global_load_dwordx4 v[116:119], v[18:19], off
	global_load_dwordx4 v[212:215], v[18:19], off offset:1024
	v_lshl_add_u64 v[18:19], v[18:19], 0, s[82:83]
	global_load_dwordx4 v[120:123], v[18:19], off
	global_load_dwordx4 v[216:219], v[18:19], off offset:1024
	v_lshl_add_u64 v[18:19], v[18:19], 0, s[82:83]
	global_load_dwordx4 v[124:127], v[18:19], off
	global_load_dwordx4 v[220:223], v[18:19], off offset:1024
	v_lshl_add_u64 v[18:19], v[18:19], 0, s[82:83]
	global_load_dwordx4 v[128:131], v[18:19], off
	global_load_dwordx4 v[224:227], v[18:19], off offset:1024
	v_lshl_add_u64 v[18:19], v[18:19], 0, s[82:83]
	global_load_dwordx4 v[132:135], v[18:19], off
	global_load_dwordx4 v[228:231], v[18:19], off offset:1024
	v_mov_b32_e32 v136, 0
	v_mov_b32_e32 v137, 0
	v_mov_b32_e32 v138, 0
	v_mov_b32_e32 v139, 0
	v_mov_b32_e32 v140, 0
	v_mov_b32_e32 v141, 0
	v_mov_b32_e32 v142, 0
	v_mov_b32_e32 v143, 0
	s_waitcnt vmcnt(0)
	v_pk_add_f32 v[138:139], v[138:139], v[94:95]
	v_pk_add_f32 v[136:137], v[136:137], v[92:93]
	v_pk_add_f32 v[142:143], v[142:143], v[190:191]
	v_pk_add_f32 v[140:141], v[140:141], v[188:189]
	v_pk_add_f32 v[138:139], v[138:139], v[98:99]
	v_pk_add_f32 v[136:137], v[136:137], v[96:97]
	v_pk_add_f32 v[142:143], v[142:143], v[194:195]
	v_pk_add_f32 v[140:141], v[140:141], v[192:193]
	v_pk_add_f32 v[138:139], v[138:139], v[102:103]
	v_pk_add_f32 v[136:137], v[136:137], v[100:101]
	v_pk_add_f32 v[142:143], v[142:143], v[198:199]
	v_pk_add_f32 v[140:141], v[140:141], v[196:197]
	v_pk_add_f32 v[138:139], v[138:139], v[106:107]
	v_pk_add_f32 v[136:137], v[136:137], v[104:105]
	v_pk_add_f32 v[142:143], v[142:143], v[202:203]
	v_pk_add_f32 v[140:141], v[140:141], v[200:201]
	v_pk_add_f32 v[138:139], v[138:139], v[110:111]
	v_pk_add_f32 v[136:137], v[136:137], v[108:109]
	v_pk_add_f32 v[142:143], v[142:143], v[206:207]
	v_pk_add_f32 v[140:141], v[140:141], v[204:205]
	v_pk_add_f32 v[138:139], v[138:139], v[114:115]
	v_pk_add_f32 v[136:137], v[136:137], v[112:113]
	v_pk_add_f32 v[142:143], v[142:143], v[210:211]
	v_pk_add_f32 v[140:141], v[140:141], v[208:209]
	v_pk_add_f32 v[138:139], v[138:139], v[118:119]
	v_pk_add_f32 v[136:137], v[136:137], v[116:117]
	v_pk_add_f32 v[142:143], v[142:143], v[214:215]
	v_pk_add_f32 v[140:141], v[140:141], v[212:213]
	v_pk_add_f32 v[138:139], v[138:139], v[122:123]
	v_pk_add_f32 v[136:137], v[136:137], v[120:121]
	v_pk_add_f32 v[142:143], v[142:143], v[218:219]
	v_pk_add_f32 v[140:141], v[140:141], v[216:217]
	v_pk_add_f32 v[138:139], v[138:139], v[126:127]
	v_pk_add_f32 v[136:137], v[136:137], v[124:125]
	v_pk_add_f32 v[142:143], v[142:143], v[222:223]
	v_pk_add_f32 v[140:141], v[140:141], v[220:221]
	v_pk_add_f32 v[138:139], v[138:139], v[130:131]
	v_pk_add_f32 v[136:137], v[136:137], v[128:129]
	v_pk_add_f32 v[142:143], v[142:143], v[226:227]
	v_pk_add_f32 v[140:141], v[140:141], v[224:225]
	v_pk_add_f32 v[138:139], v[138:139], v[134:135]
	v_pk_add_f32 v[136:137], v[136:137], v[132:133]
	v_pk_add_f32 v[142:143], v[142:143], v[230:231]
	v_pk_add_f32 v[140:141], v[140:141], v[228:229]
	v_pk_mul_f32 v[154:155], v[154:155], 0.5 op_sel_hi:[1,0]
	v_pk_mul_f32 v[152:153], v[152:153], 0.5 op_sel_hi:[1,0]
	v_pk_fma_f32 v[14:15], v[138:139], v[154:155], v[14:15]
; __device__ __forceinline__ void phase_norm(PP P, int l, int which, int nsl, const float* fgate, float fscale, const Ids I) {
;     ...
;                 for (int i = 0; i < 4; ++i) { f32x4 a = (f32x4){0.f, 0.f, 0.f, 0.f};
;                     for (int sl = 0; sl < nsl; ++sl) a += *(const f32x4*)(pp + (size_t)sl * MTS * D + 256 * i);
;                     v[j][i] += (*(const f32x4*)(gp + 256 * i) * fscale) * a;
	v_pk_fma_f32 v[12:13], v[136:137], v[152:153], v[12:13]
	v_pk_mul_f32 v[158:159], v[158:159], 0.5 op_sel_hi:[1,0]
	v_pk_mul_f32 v[156:157], v[156:157], 0.5 op_sel_hi:[1,0]
	v_pk_fma_f32 v[10:11], v[142:143], v[158:159], v[10:11]
	v_pk_fma_f32 v[8:9], v[140:141], v[156:157], v[8:9]
	v_mov_b32_e32 v18, v20
	v_mov_b32_e32 v19, v21
	global_load_dwordx4 v[92:95], v[18:19], off offset:2048
	global_load_dwordx4 v[188:191], v[18:19], off offset:3072
	v_lshl_add_u64 v[18:19], v[18:19], 0, s[82:83]
	global_load_dwordx4 v[96:99], v[18:19], off offset:2048
	global_load_dwordx4 v[192:195], v[18:19], off offset:3072
	v_lshl_add_u64 v[18:19], v[18:19], 0, s[82:83]
	global_load_dwordx4 v[100:103], v[18:19], off offset:2048
	global_load_dwordx4 v[196:199], v[18:19], off offset:3072
	v_lshl_add_u64 v[18:19], v[18:19], 0, s[82:83]
	global_load_dwordx4 v[104:107], v[18:19], off offset:2048
	global_load_dwordx4 v[200:203], v[18:19], off offset:3072
	v_lshl_add_u64 v[18:19], v[18:19], 0, s[82:83]
	global_load_dwordx4 v[108:111], v[18:19], off offset:2048
	global_load_dwordx4 v[204:207], v[18:19], off offset:3072
	v_lshl_add_u64 v[18:19], v[18:19], 0, s[82:83]
	global_load_dwordx4 v[112:115], v[18:19], off offset:2048
	global_load_dwordx4 v[208:211], v[18:19], off offset:3072
	v_lshl_add_u64 v[18:19], v[18:19], 0, s[82:83]
	global_load_dwordx4 v[116:119], v[18:19], off offset:2048
	global_load_dwordx4 v[212:215], v[18:19], off offset:3072
	v_lshl_add_u64 v[18:19], v[18:19], 0, s[82:83]
	global_load_dwordx4 v[120:123], v[18:19], off offset:2048
	global_load_dwordx4 v[216:219], v[18:19], off offset:3072
	v_lshl_add_u64 v[18:19], v[18:19], 0, s[82:83]
	global_load_dwordx4 v[124:127], v[18:19], off offset:2048
	global_load_dwordx4 v[220:223], v[18:19], off offset:3072
	v_lshl_add_u64 v[18:19], v[18:19], 0, s[82:83]
	global_load_dwordx4 v[128:131], v[18:19], off offset:2048
	global_load_dwordx4 v[224:227], v[18:19], off offset:3072
	v_lshl_add_u64 v[18:19], v[18:19], 0, s[82:83]
	global_load_dwordx4 v[132:135], v[18:19], off offset:2048
	global_load_dwordx4 v[228:231], v[18:19], off offset:3072
	v_mov_b32_e32 v136, 0
	v_mov_b32_e32 v137, 0
	v_mov_b32_e32 v138, 0
	v_mov_b32_e32 v139, 0
	v_mov_b32_e32 v140, 0
	v_mov_b32_e32 v141, 0
	v_mov_b32_e32 v142, 0
	v_mov_b32_e32 v143, 0
	s_waitcnt vmcnt(0)
	v_pk_add_f32 v[138:139], v[138:139], v[94:95]
	v_pk_add_f32 v[136:137], v[136:137], v[92:93]
	v_pk_add_f32 v[142:143], v[142:143], v[190:191]
	v_pk_add_f32 v[140:141], v[140:141], v[188:189]
	v_pk_add_f32 v[138:139], v[138:139], v[98:99]
	v_pk_add_f32 v[136:137], v[136:137], v[96:97]
	v_pk_add_f32 v[142:143], v[142:143], v[194:195]
	v_pk_add_f32 v[140:141], v[140:141], v[192:193]
	v_pk_add_f32 v[138:139], v[138:139], v[102:103]
	v_pk_add_f32 v[136:137], v[136:137], v[100:101]
	v_pk_add_f32 v[142:143], v[142:143], v[198:199]
	v_pk_add_f32 v[140:141], v[140:141], v[196:197]
	v_pk_add_f32 v[138:139], v[138:139], v[106:107]
	v_pk_add_f32 v[136:137], v[136:137], v[104:105]
	v_pk_add_f32 v[142:143], v[142:143], v[202:203]
	v_pk_add_f32 v[140:141], v[140:141], v[200:201]
	v_pk_add_f32 v[138:139], v[138:139], v[110:111]
	v_pk_add_f32 v[136:137], v[136:137], v[108:109]
	v_pk_add_f32 v[142:143], v[142:143], v[206:207]
	v_pk_add_f32 v[140:141], v[140:141], v[204:205]
	v_pk_add_f32 v[138:139], v[138:139], v[114:115]
	v_pk_add_f32 v[136:137], v[136:137], v[112:113]
	v_pk_add_f32 v[142:143], v[142:143], v[210:211]
	v_pk_add_f32 v[140:141], v[140:141], v[208:209]
	v_pk_add_f32 v[138:139], v[138:139], v[118:119]
	v_pk_add_f32 v[136:137], v[136:137], v[116:117]
	v_pk_add_f32 v[142:143], v[142:143], v[214:215]
	v_pk_add_f32 v[140:141], v[140:141], v[212:213]
	v_pk_add_f32 v[138:139], v[138:139], v[122:123]
	v_pk_add_f32 v[136:137], v[136:137], v[120:121]
	v_pk_add_f32 v[142:143], v[142:143], v[218:219]
	v_pk_add_f32 v[140:141], v[140:141], v[216:217]
	v_pk_add_f32 v[138:139], v[138:139], v[126:127]
	v_pk_add_f32 v[136:137], v[136:137], v[124:125]
	v_pk_add_f32 v[142:143], v[142:143], v[222:223]
	v_pk_add_f32 v[140:141], v[140:141], v[220:221]
	v_pk_add_f32 v[138:139], v[138:139], v[130:131]
	v_pk_add_f32 v[136:137], v[136:137], v[128:129]
	v_pk_add_f32 v[142:143], v[142:143], v[226:227]
	v_pk_add_f32 v[140:141], v[140:141], v[224:225]
	v_pk_add_f32 v[138:139], v[138:139], v[134:135]
	v_pk_add_f32 v[136:137], v[136:137], v[132:133]
	v_pk_add_f32 v[142:143], v[142:143], v[230:231]
	v_pk_add_f32 v[140:141], v[140:141], v[228:229]
	v_pk_mul_f32 v[162:163], v[162:163], 0.5 op_sel_hi:[1,0]
	v_pk_mul_f32 v[160:161], v[160:161], 0.5 op_sel_hi:[1,0]
	v_pk_fma_f32 v[6:7], v[138:139], v[162:163], v[6:7]
	v_pk_fma_f32 v[4:5], v[136:137], v[160:161], v[4:5]
	v_pk_mul_f32 v[166:167], v[166:167], 0.5 op_sel_hi:[1,0]
	v_pk_mul_f32 v[164:165], v[164:165], 0.5 op_sel_hi:[1,0]
	v_pk_fma_f32 v[2:3], v[142:143], v[166:167], v[2:3]
	v_pk_fma_f32 v[0:1], v[140:141], v[164:165], v[0:1]

; __device__ __forceinline__ float row16_allsum(float x) {
;     x += dpp_mov<0xB1>(x); x += dpp_mov<0x4E>(x); x += dpp_mov<0x141>(x); x += dpp_mov<0x140>(x); return x;
; }
; __device__ __forceinline__ float wave_sum(float x) {
;     x = row16_allsum(x);
;     const float a = __builtin_bit_cast(float, __builtin_amdgcn_readlane(__builtin_bit_cast(int, x), 0)), b = __builtin_bit_cast(float, __builtin_amdgcn_readlane(__builtin_bit_cast(int, x), 16)),
;                 c = __builtin_bit_cast(float, __builtin_amdgcn_readlane(__builtin_bit_cast(int, x), 32)), d = __builtin_bit_cast(float, __builtin_amdgcn_readlane(__builtin_bit_cast(int, x), 48));
;     return (a + b) + (c + d);
; __device__ __forceinline__ void phase_norm(PP P, int l, int which, int nsl, const float* fgate, float fscale, const Ids I) {
;     ...
;         for (int j = 0; j < 2; ++j) { float a = 0.f;
; #pragma unroll
;             for (int i = 0; i < 4; ++i) a += v[j][i][0] * v[j][i][0] + v[j][i][1] * v[j][i][1] + v[j][i][2] * v[j][i][2] + v[j][i][3] * v[j][i][3];
;             ss[j] = wave_sum(a); }
; #pragma unroll
;         for (int j = 0; j < 2; ++j) { const int row = rows[j];
;             if (j == 1 && row == row0) continue;
;             const float rstd = rsqrtf(ss[j] * (1.0f / 1024.0f) + 1e-6f);
;             if (which == 3) {
; #pragma unroll
;                 for (int i = 0; i < 4; ++i) { const int col = lane * 4 + 256 * i; const f32x4 g4 = *(const f32x4*)(gamma + col); *(f32x4*)(xb + (size_t)row * D + col) = v[j][i] * rstd * g4; }
.LBB0_25:
	s_waitcnt vmcnt(0)
	v_mov_b32_e32 v34, v9
	v_mov_b32_e32 v35, v13
	v_mov_b32_e32 v32, v8
	v_mov_b32_e32 v33, v12
	v_pk_mul_f32 v[34:35], v[34:35], v[34:35]
	s_waitcnt vmcnt(4)
	v_mov_b32_e32 v48, v1
	v_pk_fma_f32 v[32:33], v[32:33], v[32:33], v[34:35]
	v_mov_b32_e32 v34, v10
	v_mov_b32_e32 v35, v14
	v_pk_fma_f32 v[32:33], v[34:35], v[34:35], v[32:33]
	v_mov_b32_e32 v34, v11
	v_mov_b32_e32 v35, v15
	v_mov_b32_e32 v49, v5
	v_pk_fma_f32 v[32:33], v[34:35], v[34:35], v[32:33]
	v_mov_b32_e32 v34, v0
	v_mov_b32_e32 v35, v4
	v_pk_mul_f32 v[48:49], v[48:49], v[48:49]
	v_add_f32_e32 v32, v32, v33
	v_pk_fma_f32 v[34:35], v[34:35], v[34:35], v[48:49]
	v_mov_b32_e32 v48, v2
	v_mov_b32_e32 v49, v6
	v_pk_fma_f32 v[34:35], v[48:49], v[48:49], v[34:35]
	v_mov_b32_e32 v48, v3
	v_mov_b32_e32 v49, v7
	v_pk_fma_f32 v[34:35], v[48:49], v[48:49], v[34:35]
	global_load_dwordx4 v[48:51], v[40:41], off
	v_add_f32_e32 v32, v35, v32
	v_add_f32_e32 v32, v34, v32
	s_waitcnt vmcnt(3)
	v_mul_f32_e32 v33, v25, v25
	v_fmac_f32_e32 v33, v24, v24
	v_add_f32_dpp v32, v32, v32 quad_perm:[1,0,3,2] row_mask:0xf bank_mask:0xf bound_ctrl:1
	v_fmac_f32_e32 v33, v26, v26
	v_fmac_f32_e32 v33, v27, v27
	v_add_f32_dpp v32, v32, v32 quad_perm:[2,3,0,1] row_mask:0xf bank_mask:0xf bound_ctrl:1
	s_nop 1
	v_add_f32_dpp v32, v32, v32 row_half_mirror row_mask:0xf bank_mask:0xf bound_ctrl:1
	s_nop 1
	v_add_f32_dpp v32, v32, v32 row_mirror row_mask:0xf bank_mask:0xf bound_ctrl:1
	s_nop 0
	v_readlane_b32 s12, v32, 0
	v_readlane_b32 s14, v32, 16
	v_readlane_b32 s13, v32, 32
	v_readlane_b32 s15, v32, 48
	v_mul_f32_e32 v32, v29, v29
	v_fmac_f32_e32 v32, v28, v28
	v_fmac_f32_e32 v32, v30, v30
	v_fmac_f32_e32 v32, v31, v31
	v_add_f32_e32 v32, v33, v32
	s_waitcnt vmcnt(2)
	v_mul_f32_e32 v33, v21, v21
	v_fmac_f32_e32 v33, v20, v20
	v_fmac_f32_e32 v33, v22, v22
	v_fmac_f32_e32 v33, v23, v23
	v_add_f32_e32 v32, v33, v32
	s_waitcnt vmcnt(1)
	v_mul_f32_e32 v33, v17, v17
	v_fmac_f32_e32 v33, v16, v16
	v_fmac_f32_e32 v33, v18, v18
	v_fmac_f32_e32 v33, v19, v19
	v_add_f32_e32 v32, v33, v32
	v_mov_b32_e32 v33, s15
	s_nop 0
	v_add_f32_dpp v32, v32, v32 quad_perm:[1,0,3,2] row_mask:0xf bank_mask:0xf bound_ctrl:1
	s_nop 1
	v_add_f32_dpp v32, v32, v32 quad_perm:[2,3,0,1] row_mask:0xf bank_mask:0xf bound_ctrl:1
	s_nop 1
	v_add_f32_dpp v32, v32, v32 row_half_mirror row_mask:0xf bank_mask:0xf bound_ctrl:1
	s_nop 1
	v_add_f32_dpp v32, v32, v32 row_mirror row_mask:0xf bank_mask:0xf bound_ctrl:1
	s_nop 0
	v_readlane_b32 s8, v32, 0
	v_readlane_b32 s3, v32, 16
	v_readlane_b32 s9, v32, 32
	v_readlane_b32 s11, v32, 48
	v_mov_b32_e32 v32, s14
	v_pk_add_f32 v[32:33], s[12:13], v[32:33]
	s_nop 0
	v_add_f32_e32 v32, v32, v33
	v_fmamk_f32 v32, v32, 0x3a800000, v174
	v_cmp_gt_f32_e32 vcc, s58, v32
	v_mul_f32_e32 v33, 0x4b800000, v32
	s_nop 0
	v_cndmask_b32_e32 v32, v32, v33, vcc
	v_rsq_f32_e32 v32, v32
	s_nop 0
	v_mul_f32_e32 v33, 0x45800000, v32
	v_cndmask_b32_e32 v32, v32, v33, vcc
	v_pk_mul_f32 v[12:13], v[12:13], v[32:33] op_sel_hi:[1,0]
	v_pk_mul_f32 v[14:15], v[14:15], v[32:33] op_sel_hi:[1,0]
	v_pk_mul_f32 v[10:11], v[10:11], v[32:33] op_sel_hi:[1,0]
	v_pk_mul_f32 v[8:9], v[8:9], v[32:33] op_sel_hi:[1,0]
	v_pk_mul_f32 v[6:7], v[6:7], v[32:33] op_sel_hi:[1,0]
	v_pk_mul_f32 v[4:5], v[4:5], v[32:33] op_sel_hi:[1,0]
	v_pk_mul_f32 v[2:3], v[2:3], v[32:33] op_sel_hi:[1,0]
	v_pk_mul_f32 v[0:1], v[0:1], v[32:33] op_sel_hi:[1,0]
	s_andn2_b64 vcc, exec, s[6:7]
	s_waitcnt vmcnt(0)
	v_pk_mul_f32 v[14:15], v[50:51], v[14:15]
	v_pk_mul_f32 v[12:13], v[48:49], v[12:13]
	global_store_dwordx4 v[44:45], v[12:15], off offset:-3072
	global_load_dwordx4 v[12:15], v[40:41], off offset:1024
	s_waitcnt vmcnt(0)
	v_pk_mul_f32 v[8:9], v[12:13], v[8:9]
	v_pk_mul_f32 v[10:11], v[14:15], v[10:11]
	global_store_dwordx4 v[44:45], v[8:11], off offset:-2048
	global_load_dwordx4 v[8:11], v[40:41], off offset:2048
	s_waitcnt vmcnt(0)
	v_pk_mul_f32 v[4:5], v[8:9], v[4:5]
	v_pk_mul_f32 v[6:7], v[10:11], v[6:7]
	global_store_dwordx4 v[44:45], v[4:7], off offset:-1024
	global_load_dwordx4 v[4:7], v[40:41], off offset:3072
	s_waitcnt vmcnt(0)
	v_pk_mul_f32 v[0:1], v[0:1], v[4:5]
	v_pk_mul_f32 v[2:3], v[2:3], v[6:7]
	global_store_dwordx4 v[44:45], v[0:3], off
	s_cbranch_vccnz .LBB0_20
	s_nop 0
	v_mov_b32_e32 v0, s3
	v_mov_b32_e32 v1, s11
	v_pk_add_f32 v[0:1], s[8:9], v[0:1]
	s_nop 0
	v_add_f32_e32 v0, v0, v1
	v_fmamk_f32 v0, v0, 0x3a800000, v174
	v_cmp_gt_f32_e32 vcc, s58, v0
	v_mul_f32_e32 v1, 0x4b800000, v0
	s_nop 0
	v_cndmask_b32_e32 v0, v0, v1, vcc
	v_rsq_f32_e32 v0, v0
	s_nop 0
	v_mul_f32_e32 v1, 0x45800000, v0
	v_cndmask_b32_e32 v4, v0, v1, vcc
	global_load_dwordx4 v[0:3], v[40:41], off
	v_pk_mul_f32 v[6:7], v[28:29], v[4:5] op_sel_hi:[1,0]
	v_pk_mul_f32 v[8:9], v[30:31], v[4:5] op_sel_hi:[1,0]
	s_waitcnt vmcnt(0)
	v_pk_mul_f32 v[0:1], v[6:7], v[0:1]
	v_pk_mul_f32 v[2:3], v[8:9], v[2:3]
	global_store_dwordx4 v[46:47], v[0:3], off
	global_load_dwordx4 v[0:3], v[40:41], off offset:1024
	v_pk_mul_f32 v[6:7], v[26:27], v[4:5] op_sel_hi:[1,0]
	v_pk_mul_f32 v[8:9], v[24:25], v[4:5] op_sel_hi:[1,0]
	s_waitcnt vmcnt(0)
	v_pk_mul_f32 v[2:3], v[6:7], v[2:3]
	v_pk_mul_f32 v[0:1], v[8:9], v[0:1]
	global_store_dwordx4 v[46:47], v[0:3], off offset:1024
	global_load_dwordx4 v[0:3], v[40:41], off offset:2048
	v_pk_mul_f32 v[6:7], v[22:23], v[4:5] op_sel_hi:[1,0]
	v_pk_mul_f32 v[8:9], v[20:21], v[4:5] op_sel_hi:[1,0]
	s_waitcnt vmcnt(0)
	v_pk_mul_f32 v[2:3], v[6:7], v[2:3]
	v_pk_mul_f32 v[0:1], v[8:9], v[0:1]
	global_store_dwordx4 v[46:47], v[0:3], off offset:2048
	global_load_dwordx4 v[0:3], v[40:41], off offset:3072
	v_pk_mul_f32 v[6:7], v[18:19], v[4:5] op_sel_hi:[1,0]
	v_pk_mul_f32 v[4:5], v[16:17], v[4:5] op_sel_hi:[1,0]
	s_waitcnt vmcnt(0)
	v_pk_mul_f32 v[2:3], v[6:7], v[2:3]
	v_pk_mul_f32 v[0:1], v[4:5], v[0:1]
	global_store_dwordx4 v[46:47], v[0:3], off offset:3072
	s_branch .LBB0_20
	s_nop 0
	s_nop 0
	s_nop 0
	s_nop 0
	s_nop 0
	s_nop 0
	s_nop 0
	s_nop 0
	s_nop 0
	s_nop 0
	s_nop 0
	s_nop 0
	s_nop 0
	s_nop 0
	s_nop 0
	s_nop 0
	s_nop 0
	s_nop 0
	s_nop 0
	s_nop 0
	s_nop 0
	s_nop 0
	s_nop 0
	s_nop 0
	s_nop 0
	s_nop 0
